# v42 + GDN chunk-local units touch the next unit's conv input rows during the forward substitution (L2 warm-up of step-1 loads)
# baseline (speedup 1.0000x reference)
; __device__ __forceinline__ void lds_barrier() { asm volatile("s_waitcnt lgkmcnt(0)" ::: "memory"); __builtin_amdgcn_s_barrier(); asm volatile("" ::: "memory"); }
; __device__ __forceinline__ void gdn_local_unit(LAS unsigned char* lds, const GdnP& P, int unit, const int tid, const int pf) {
;     ...
;         const int c8 = tid & 15, which = (tid >> 4) % 3, tseg = tid / 48, t0 = tseg * 8, col = which * 1024 + h * 128 + c8 * 8;
;         float wg[4][8];
; #pragma unroll
;         for (int i = 0; i < 4; ++i) { const f32x4 w0 = *(const f32x4*)(P.conv + i * 3072 + col), w1 = *(const f32x4*)(P.conv + i * 3072 + col + 4);
;             wg[i][0] = w0.x; wg[i][1] = w0.y; wg[i][2] = w0.z; wg[i][3] = w0.w; wg[i][4] = w1.x; wg[i][5] = w1.y; wg[i][6] = w1.z; wg[i][7] = w1.w; }
;         u32x4 raw[11];
; #pragma unroll
;         for (int r = 0; r < 11; ++r) { const int tt = t0 - 3 + r; raw[r] = (u32x4){0u, 0u, 0u, 0u};
;             if (tt >= 0) raw[r] = *(const u32x4*)(P.proj + (size_t)(row0 + tt) * NIN + C_GDN + col);
;     ...
;     lds_barrier();
;     if (tid < 256 && !(pf & 2)) {
;         const int col = tid; f32x2 sol2[32];
;         if (col < 128) {
; #pragma unroll
;             for (int t = 0; t < 64; ++t) sol2[t >> 1][t & 1] = Vs[t * 128 + col] * beta[t];
;         } else {
; #pragma unroll
;             for (int t = 0; t < 64; ++t) sol2[t >> 1][t & 1] = Ks[t * 132 + col - 128] * rk[t] * beta[t] * eG[t];
.LBB0_1010:
	s_waitcnt lgkmcnt(0)
	s_barrier
	v_readlane_b32 s0, v253, 16
	s_add_i32 s0, s80, s0
	s_cmpk_gt_i32 s0, 0x7ff
	s_cbranch_scc1 .Lcpf_skip
	s_mov_b64 s[40:41], exec
	s_and_b64 exec, exec, s[76:77]
	s_cbranch_execz .Lcpf_done
	s_ashr_i32 s1, s0, 3
	s_and_b32 s2, s0, 7
	s_lshl_b32 s1, s1, 6
	v_lshl_or_b32 v246, s2, 7, v99
	v_mov_b32_e32 v247, 0
	v_add_u32_e32 v248, s1, v169
	v_mov_b64_e32 v[250:251], s[68:69]
	s_mov_b64 s[62:63], 0x5a00
	v_mad_i64_i32 v[250:251], s[42:43], v248, s87, v[250:251]
	v_lshl_add_u64 v[250:251], v[246:247], 1, v[250:251]
	s_mov_b64 s[2:3], 0x1000
	v_lshl_add_u64 v[250:251], v[250:251], 0, s[2:3]
	global_load_dword v249, v[250:251], off offset:2048
	v_lshl_add_u64 v[250:251], v[250:251], 0, s[62:63]
	global_load_dword v249, v[250:251], off offset:2048
	v_lshl_add_u64 v[250:251], v[250:251], 0, s[62:63]
	global_load_dword v249, v[250:251], off offset:2048
	v_lshl_add_u64 v[250:251], v[250:251], 0, s[62:63]
	global_load_dword v249, v[250:251], off offset:2048
	v_lshl_add_u64 v[250:251], v[250:251], 0, s[62:63]
	global_load_dword v249, v[250:251], off offset:2048
	v_lshl_add_u64 v[250:251], v[250:251], 0, s[62:63]
	global_load_dword v249, v[250:251], off offset:2048
	v_lshl_add_u64 v[250:251], v[250:251], 0, s[62:63]
	global_load_dword v249, v[250:251], off offset:2048
	v_lshl_add_u64 v[250:251], v[250:251], 0, s[62:63]
	global_load_dword v249, v[250:251], off offset:2048
	v_lshl_add_u64 v[250:251], v[250:251], 0, s[62:63]
	global_load_dword v249, v[250:251], off offset:2048
	v_lshl_add_u64 v[250:251], v[250:251], 0, s[62:63]
	global_load_dword v249, v[250:251], off offset:2048
	v_lshl_add_u64 v[250:251], v[250:251], 0, s[62:63]
	global_load_dword v249, v[250:251], off offset:2048
.Lcpf_done:
	s_mov_b64 exec, s[40:41]
.Lcpf_skip:
	s_and_saveexec_b64 s[0:1], s[78:79]
	s_xor_b64 s[0:1], exec, s[0:1]
	s_cbranch_execz .LBB0_1020
	s_and_saveexec_b64 s[40:41], s[30:31]
	s_cbranch_execz .LBB0_1019
	ds_read_b32 v1, v130 offset:1020
	s_and_saveexec_b64 s[42:43], s[34:35]
	s_cbranch_execz .LBB0_1017
	s_lshl_b32 s2, s93, 7
	v_add_u32_e32 v0, s92, v203
	v_add_u32_e32 v2, v132, v204
	v_add_u32_e32 v3, v130, v206
	s_mov_b64 s[52:53], 0
	v_mov_b32_e32 v4, v202
	v_mov_b32_e32 v5, v201
